# RWKV step loops: neighbouring lgkmcnt waits merged (156 -> 153 instructions per two steps), on v27
# baseline (speedup 1.0000x reference)
.LBB0_459:
	v_add_u32_e32 v137, s14, v201
	v_add_u32_e32 v136, s14, v205
	v_pk_mul_f32 v[134:135], v[104:105], v[84:85]
	v_pk_mul_f32 v[104:105], v[104:105], v[76:77]
	v_pk_fma_f32 v[134:135], v[86:87], v[106:107], v[134:135]
	v_pk_fma_f32 v[104:105], v[78:79], v[106:107], v[104:105]
	v_pk_fma_f32 v[134:135], v[80:81], v[112:113], v[134:135]
	v_pk_fma_f32 v[104:105], v[72:73], v[112:113], v[104:105]
	v_pk_fma_f32 v[134:135], v[82:83], v[114:115], v[134:135]
	v_pk_fma_f32 v[138:139], v[74:75], v[114:115], v[104:105]
	ds_read_b128 v[104:107], v137 offset:33024
	ds_read_b128 v[112:115], v137 offset:33040
	v_add_f32_e32 v134, v134, v135
	v_add_f32_e32 v135, v138, v139
	v_pk_mul_f32 v[140:141], v[88:89], v[130:131] op_sel_hi:[1,0]
	v_add_f32_dpp v134, v134, v134 quad_perm:[1,0,3,2] row_mask:0xf bank_mask:0xf bound_ctrl:1
	v_add_f32_dpp v135, v135, v135 quad_perm:[1,0,3,2] row_mask:0xf bank_mask:0xf bound_ctrl:1
	v_pk_mul_f32 v[142:143], v[90:91], v[130:131] op_sel_hi:[1,0]
	v_add_f32_dpp v134, v134, v134 quad_perm:[2,3,0,1] row_mask:0xf bank_mask:0xf bound_ctrl:1
	v_add_f32_dpp v135, v135, v135 quad_perm:[2,3,0,1] row_mask:0xf bank_mask:0xf bound_ctrl:1
	v_pk_mul_f32 v[144:145], v[96:97], v[130:131] op_sel_hi:[1,0]
	v_pk_mul_f32 v[146:147], v[98:99], v[130:131] op_sel_hi:[1,0]
	v_pk_mul_f32 v[164:165], v[88:89], v[132:133] op_sel_hi:[1,0]
	v_add_f32_dpp v134, v134, v134 row_half_mirror row_mask:0xf bank_mask:0xf bound_ctrl:1
	v_add_f32_dpp v138, v135, v135 row_half_mirror row_mask:0xf bank_mask:0xf bound_ctrl:1
	v_pk_mul_f32 v[166:167], v[90:91], v[132:133] op_sel_hi:[1,0]
	v_pk_mul_f32 v[168:169], v[96:97], v[132:133] op_sel_hi:[1,0]
	v_pk_mul_f32 v[132:133], v[98:99], v[132:133] op_sel_hi:[1,0]
	ds_read_b128 v[96:99], v137 offset:8448
	ds_read_b128 v[88:91], v137 offset:8464
	ds_read2_b32 v[130:131], v136 offset1:32
	s_waitcnt lgkmcnt(10)
	v_pk_fma_f32 v[140:141], v[134:135], v[92:93], v[140:141] op_sel_hi:[0,1,1]
	v_pk_fma_f32 v[142:143], v[134:135], v[94:95], v[142:143] op_sel_hi:[0,1,1]
	v_pk_fma_f32 v[144:145], v[134:135], v[100:101], v[144:145] op_sel_hi:[0,1,1]
	v_pk_fma_f32 v[134:135], v[134:135], v[102:103], v[146:147] op_sel_hi:[0,1,1]
	v_pk_fma_f32 v[146:147], v[138:139], v[92:93], v[164:165] op_sel_hi:[0,1,1]
	v_pk_fma_f32 v[164:165], v[138:139], v[94:95], v[166:167] op_sel_hi:[0,1,1]
	v_pk_fma_f32 v[132:133], v[138:139], v[102:103], v[132:133] op_sel_hi:[0,1,1]
	v_pk_fma_f32 v[84:85], v[84:85], v[108:109], v[140:141]
	v_pk_fma_f32 v[108:109], v[76:77], v[108:109], v[146:147]
	v_pk_fma_f32 v[166:167], v[138:139], v[100:101], v[168:169] op_sel_hi:[0,1,1]
	ds_read_b128 v[100:103], v137 offset:41216
	ds_read_b128 v[92:95], v137 offset:41232
	v_pk_fma_f32 v[86:87], v[86:87], v[110:111], v[142:143]
	s_waitcnt lgkmcnt(9)
	v_pk_fma_f32 v[82:83], v[82:83], v[118:119], v[134:135]
	v_pk_fma_f32 v[110:111], v[78:79], v[110:111], v[164:165]
	v_pk_fma_f32 v[118:119], v[74:75], v[118:119], v[132:133]
	v_pk_mul_f32 v[132:133], v[120:121], v[84:85]
	v_pk_mul_f32 v[120:121], v[120:121], v[108:109]
	v_pk_fma_f32 v[80:81], v[80:81], v[116:117], v[144:145]
	v_pk_fma_f32 v[116:117], v[72:73], v[116:117], v[166:167]
	v_pk_fma_f32 v[132:133], v[86:87], v[122:123], v[132:133]
	v_pk_fma_f32 v[120:121], v[110:111], v[122:123], v[120:121]
	v_pk_fma_f32 v[132:133], v[80:81], v[124:125], v[132:133]
	v_pk_fma_f32 v[120:121], v[116:117], v[124:125], v[120:121]
	v_pk_fma_f32 v[132:133], v[82:83], v[126:127], v[132:133]
	v_pk_fma_f32 v[134:135], v[118:119], v[126:127], v[120:121]
	v_add_f32_e32 v132, v132, v133
	v_add_f32_e32 v133, v134, v135
	ds_read_b128 v[76:79], v137 offset:24832
	v_add_f32_dpp v132, v132, v132 quad_perm:[1,0,3,2] row_mask:0xf bank_mask:0xf bound_ctrl:1
	v_add_f32_dpp v133, v133, v133 quad_perm:[1,0,3,2] row_mask:0xf bank_mask:0xf bound_ctrl:1
	ds_read_b128 v[72:75], v137 offset:24848
	v_add_f32_dpp v132, v132, v132 quad_perm:[2,3,0,1] row_mask:0xf bank_mask:0xf bound_ctrl:1
	v_add_f32_dpp v133, v133, v133 quad_perm:[2,3,0,1] row_mask:0xf bank_mask:0xf bound_ctrl:1
	ds_read_b128 v[124:127], v137 offset:256
	v_add_f32_dpp v132, v132, v132 row_half_mirror row_mask:0xf bank_mask:0xf bound_ctrl:1
	v_add_f32_dpp v133, v133, v133 row_half_mirror row_mask:0xf bank_mask:0xf bound_ctrl:1
	ds_read_b128 v[120:123], v137 offset:272
	ds_write_b32 v136, v132 offset:32512
	ds_write_b32 v136, v133 offset:32640
	s_waitcnt lgkmcnt(11)
	v_pk_mul_f32 v[132:133], v[104:105], v[84:85]
	v_pk_mul_f32 v[104:105], v[104:105], v[108:109]
	v_pk_fma_f32 v[132:133], v[86:87], v[106:107], v[132:133]
	v_pk_fma_f32 v[104:105], v[110:111], v[106:107], v[104:105]
	v_pk_fma_f32 v[132:133], v[80:81], v[112:113], v[132:133]
	v_pk_fma_f32 v[104:105], v[116:117], v[112:113], v[104:105]
	v_pk_fma_f32 v[132:133], v[82:83], v[114:115], v[132:133]
	v_pk_fma_f32 v[134:135], v[118:119], v[114:115], v[104:105]
	ds_read_b128 v[104:107], v137 offset:33280
	ds_read_b128 v[112:115], v137 offset:33296
	v_add_f32_e32 v132, v132, v133
	v_add_f32_e32 v133, v134, v135
	s_waitcnt lgkmcnt(10)
	v_pk_mul_f32 v[138:139], v[96:97], v[130:131] op_sel_hi:[1,0]
	v_add_f32_dpp v132, v132, v132 quad_perm:[1,0,3,2] row_mask:0xf bank_mask:0xf bound_ctrl:1
	v_add_f32_dpp v133, v133, v133 quad_perm:[1,0,3,2] row_mask:0xf bank_mask:0xf bound_ctrl:1
	v_pk_mul_f32 v[140:141], v[98:99], v[130:131] op_sel_hi:[1,0]
	v_pk_mul_f32 v[142:143], v[88:89], v[130:131] op_sel_hi:[1,0]
	v_pk_mul_f32 v[144:145], v[90:91], v[130:131] op_sel_hi:[1,0]
	v_mov_b32_e32 v130, v131
	v_add_f32_dpp v132, v132, v132 quad_perm:[2,3,0,1] row_mask:0xf bank_mask:0xf bound_ctrl:1
	v_add_f32_dpp v133, v133, v133 quad_perm:[2,3,0,1] row_mask:0xf bank_mask:0xf bound_ctrl:1
	v_pk_mul_f32 v[146:147], v[96:97], v[130:131] op_sel_hi:[1,0]
	v_add_f32_dpp v132, v132, v132 row_half_mirror row_mask:0xf bank_mask:0xf bound_ctrl:1
	v_add_f32_dpp v134, v133, v133 row_half_mirror row_mask:0xf bank_mask:0xf bound_ctrl:1
	v_pk_mul_f32 v[164:165], v[98:99], v[130:131] op_sel_hi:[1,0]
	s_waitcnt lgkmcnt(8)
	v_pk_fma_f32 v[138:139], v[132:133], v[100:101], v[138:139] op_sel_hi:[0,1,1]
	v_pk_fma_f32 v[140:141], v[132:133], v[102:103], v[140:141] op_sel_hi:[0,1,1]
	v_pk_fma_f32 v[142:143], v[132:133], v[92:93], v[142:143] op_sel_hi:[0,1,1]
	v_pk_fma_f32 v[132:133], v[132:133], v[94:95], v[144:145] op_sel_hi:[0,1,1]
	v_pk_fma_f32 v[144:145], v[134:135], v[100:101], v[146:147] op_sel_hi:[0,1,1]
	v_pk_mul_f32 v[166:167], v[88:89], v[130:131] op_sel_hi:[1,0]
	v_pk_fma_f32 v[146:147], v[134:135], v[102:103], v[164:165] op_sel_hi:[0,1,1]
	s_waitcnt lgkmcnt(7)
	v_pk_fma_f32 v[84:85], v[84:85], v[76:77], v[138:139]
	v_pk_fma_f32 v[76:77], v[108:109], v[76:77], v[144:145]
	v_pk_mul_f32 v[168:169], v[90:91], v[130:131] op_sel_hi:[1,0]
	ds_read_b128 v[88:91], v137 offset:8704
	ds_read_b128 v[96:99], v137 offset:8720
	ds_read2_b32 v[130:131], v136 offset0:64 offset1:96
	v_pk_fma_f32 v[164:165], v[134:135], v[92:93], v[166:167] op_sel_hi:[0,1,1]
	v_pk_fma_f32 v[86:87], v[86:87], v[78:79], v[140:141]
	s_waitcnt lgkmcnt(7)
	v_pk_fma_f32 v[82:83], v[82:83], v[74:75], v[132:133]
	v_pk_fma_f32 v[78:79], v[110:111], v[78:79], v[146:147]
	v_pk_mul_f32 v[132:133], v[124:125], v[84:85]
	v_pk_mul_f32 v[124:125], v[124:125], v[76:77]
	v_pk_fma_f32 v[134:135], v[134:135], v[94:95], v[168:169] op_sel_hi:[0,1,1]
	ds_read_b128 v[92:95], v137 offset:41472
	ds_read_b128 v[100:103], v137 offset:41488
	v_pk_fma_f32 v[80:81], v[80:81], v[72:73], v[142:143]
	v_pk_fma_f32 v[72:73], v[116:117], v[72:73], v[164:165]
	v_pk_fma_f32 v[132:133], v[86:87], v[126:127], v[132:133]
	v_pk_fma_f32 v[124:125], v[78:79], v[126:127], v[124:125]
	v_pk_fma_f32 v[74:75], v[118:119], v[74:75], v[134:135]
	v_pk_fma_f32 v[132:133], v[80:81], v[120:121], v[132:133]
	v_pk_fma_f32 v[120:121], v[72:73], v[120:121], v[124:125]
	v_pk_fma_f32 v[132:133], v[82:83], v[122:123], v[132:133]
	v_pk_fma_f32 v[134:135], v[74:75], v[122:123], v[120:121]
	v_add_f32_e32 v132, v132, v133
	v_add_f32_e32 v133, v134, v135
	ds_read_b128 v[108:111], v137 offset:25088
	v_add_f32_dpp v132, v132, v132 quad_perm:[1,0,3,2] row_mask:0xf bank_mask:0xf bound_ctrl:1
	v_add_f32_dpp v133, v133, v133 quad_perm:[1,0,3,2] row_mask:0xf bank_mask:0xf bound_ctrl:1
	ds_read_b128 v[116:119], v137 offset:25104
	v_add_f32_dpp v132, v132, v132 quad_perm:[2,3,0,1] row_mask:0xf bank_mask:0xf bound_ctrl:1
	v_add_f32_dpp v133, v133, v133 quad_perm:[2,3,0,1] row_mask:0xf bank_mask:0xf bound_ctrl:1
	ds_read_b128 v[120:123], v137 offset:512
	v_add_f32_dpp v132, v132, v132 row_half_mirror row_mask:0xf bank_mask:0xf bound_ctrl:1
	v_add_f32_dpp v133, v133, v133 row_half_mirror row_mask:0xf bank_mask:0xf bound_ctrl:1
	ds_read_b128 v[124:127], v137 offset:528
	ds_write_b32 v136, v132 offset:32768
	ds_write_b32 v136, v133 offset:32896
	s_waitcnt lgkmcnt(8)
	v_mov_b32_e32 v132, v131
	s_addk_i32 s14, 0x200
	s_cmpk_eq_i32 s14, 0x2000
	s_cbranch_scc0 .LBB0_459
	s_waitcnt lgkmcnt(0)
	s_barrier
	ds_read_b128 v[88:91], v199 offset:49152
	ds_read_b128 v[92:95], v199 offset:49168
	s_cmp_eq_u32 s2, 8
	s_waitcnt lgkmcnt(1)
	v_cvt_pk_bf16_f32 v88, v88, v89
	v_cvt_pk_bf16_f32 v89, v90, v91
	s_waitcnt lgkmcnt(0)
	v_cvt_pk_bf16_f32 v90, v92, v93
	v_lshlrev_b64 v[92:93], 10, v[128:129]
	v_cvt_pk_bf16_f32 v91, v94, v95
	v_lshl_add_u64 v[92:93], v[154:155], 0, v[92:93]
	global_store_dwordx4 v[92:93], v[88:91], off
	s_cbranch_scc1 .LBB0_463
	v_mov_b64_e32 v[106:107], v[70:71]
	v_mov_b64_e32 v[90:91], v[54:55]
	v_mov_b64_e32 v[94:95], v[58:59]
	v_mov_b64_e32 v[110:111], v[62:63]
	v_mov_b64_e32 v[114:115], v[66:67]
	v_mov_b64_e32 v[104:105], v[68:69]
	v_mov_b64_e32 v[88:89], v[52:53]
	v_mov_b64_e32 v[92:93], v[56:57]
	v_mov_b64_e32 v[108:109], v[60:61]
	v_mov_b64_e32 v[112:113], v[64:65]
	s_mov_b32 s14, s2
	s_branch .LBB0_447

.LBB0_493:
	v_add_u32_e32 v137, s14, v197
	v_add_u32_e32 v136, s14, v148
	v_pk_mul_f32 v[134:135], v[104:105], v[36:37]
	v_pk_mul_f32 v[104:105], v[104:105], v[40:41]
	v_pk_fma_f32 v[134:135], v[38:39], v[106:107], v[134:135]
	v_pk_fma_f32 v[104:105], v[42:43], v[106:107], v[104:105]
	v_pk_fma_f32 v[134:135], v[32:33], v[112:113], v[134:135]
	v_pk_fma_f32 v[104:105], v[44:45], v[112:113], v[104:105]
	v_pk_fma_f32 v[134:135], v[34:35], v[114:115], v[134:135]
	v_pk_fma_f32 v[138:139], v[46:47], v[114:115], v[104:105]
	ds_read_b128 v[104:107], v137 offset:33024
	ds_read_b128 v[112:115], v137 offset:33040
	v_add_f32_e32 v134, v134, v135
	v_add_f32_e32 v135, v138, v139
	v_pk_mul_f32 v[140:141], v[88:89], v[130:131] op_sel_hi:[1,0]
	v_add_f32_dpp v134, v134, v134 quad_perm:[1,0,3,2] row_mask:0xf bank_mask:0xf bound_ctrl:1
	v_add_f32_dpp v135, v135, v135 quad_perm:[1,0,3,2] row_mask:0xf bank_mask:0xf bound_ctrl:1
	v_pk_mul_f32 v[142:143], v[90:91], v[130:131] op_sel_hi:[1,0]
	v_add_f32_dpp v134, v134, v134 quad_perm:[2,3,0,1] row_mask:0xf bank_mask:0xf bound_ctrl:1
	v_add_f32_dpp v135, v135, v135 quad_perm:[2,3,0,1] row_mask:0xf bank_mask:0xf bound_ctrl:1
	v_pk_mul_f32 v[144:145], v[96:97], v[130:131] op_sel_hi:[1,0]
	v_pk_mul_f32 v[146:147], v[98:99], v[130:131] op_sel_hi:[1,0]
	v_pk_mul_f32 v[160:161], v[88:89], v[132:133] op_sel_hi:[1,0]
	v_add_f32_dpp v134, v134, v134 row_half_mirror row_mask:0xf bank_mask:0xf bound_ctrl:1
	v_add_f32_dpp v138, v135, v135 row_half_mirror row_mask:0xf bank_mask:0xf bound_ctrl:1
	v_pk_mul_f32 v[162:163], v[90:91], v[132:133] op_sel_hi:[1,0]
	v_pk_mul_f32 v[164:165], v[96:97], v[132:133] op_sel_hi:[1,0]
	v_pk_mul_f32 v[132:133], v[98:99], v[132:133] op_sel_hi:[1,0]
	ds_read_b128 v[96:99], v137 offset:8448
	ds_read_b128 v[88:91], v137 offset:8464
	ds_read2_b32 v[130:131], v136 offset1:32
	s_waitcnt lgkmcnt(10)
	v_pk_fma_f32 v[140:141], v[134:135], v[92:93], v[140:141] op_sel_hi:[0,1,1]
	v_pk_fma_f32 v[142:143], v[134:135], v[94:95], v[142:143] op_sel_hi:[0,1,1]
	v_pk_fma_f32 v[144:145], v[134:135], v[100:101], v[144:145] op_sel_hi:[0,1,1]
	v_pk_fma_f32 v[134:135], v[134:135], v[102:103], v[146:147] op_sel_hi:[0,1,1]
	v_pk_fma_f32 v[146:147], v[138:139], v[92:93], v[160:161] op_sel_hi:[0,1,1]
	v_pk_fma_f32 v[160:161], v[138:139], v[94:95], v[162:163] op_sel_hi:[0,1,1]
	v_pk_fma_f32 v[132:133], v[138:139], v[102:103], v[132:133] op_sel_hi:[0,1,1]
	v_pk_fma_f32 v[36:37], v[36:37], v[108:109], v[140:141]
	v_pk_fma_f32 v[108:109], v[40:41], v[108:109], v[146:147]
	v_pk_fma_f32 v[162:163], v[138:139], v[100:101], v[164:165] op_sel_hi:[0,1,1]
	ds_read_b128 v[100:103], v137 offset:41216
	ds_read_b128 v[92:95], v137 offset:41232
	v_pk_fma_f32 v[38:39], v[38:39], v[110:111], v[142:143]
	s_waitcnt lgkmcnt(9)
	v_pk_fma_f32 v[34:35], v[34:35], v[118:119], v[134:135]
	v_pk_fma_f32 v[110:111], v[42:43], v[110:111], v[160:161]
	v_pk_fma_f32 v[118:119], v[46:47], v[118:119], v[132:133]
	v_pk_mul_f32 v[132:133], v[120:121], v[36:37]
	v_pk_mul_f32 v[120:121], v[120:121], v[108:109]
	v_pk_fma_f32 v[32:33], v[32:33], v[116:117], v[144:145]
	v_pk_fma_f32 v[116:117], v[44:45], v[116:117], v[162:163]
	v_pk_fma_f32 v[132:133], v[38:39], v[122:123], v[132:133]
	v_pk_fma_f32 v[120:121], v[110:111], v[122:123], v[120:121]
	v_pk_fma_f32 v[132:133], v[32:33], v[124:125], v[132:133]
	v_pk_fma_f32 v[120:121], v[116:117], v[124:125], v[120:121]
	v_pk_fma_f32 v[132:133], v[34:35], v[126:127], v[132:133]
	v_pk_fma_f32 v[134:135], v[118:119], v[126:127], v[120:121]
	v_add_f32_e32 v132, v132, v133
	v_add_f32_e32 v133, v134, v135
	ds_read_b128 v[40:43], v137 offset:24832
	v_add_f32_dpp v132, v132, v132 quad_perm:[1,0,3,2] row_mask:0xf bank_mask:0xf bound_ctrl:1
	v_add_f32_dpp v133, v133, v133 quad_perm:[1,0,3,2] row_mask:0xf bank_mask:0xf bound_ctrl:1
	ds_read_b128 v[44:47], v137 offset:24848
	v_add_f32_dpp v132, v132, v132 quad_perm:[2,3,0,1] row_mask:0xf bank_mask:0xf bound_ctrl:1
	v_add_f32_dpp v133, v133, v133 quad_perm:[2,3,0,1] row_mask:0xf bank_mask:0xf bound_ctrl:1
	ds_read_b128 v[124:127], v137 offset:256
	v_add_f32_dpp v132, v132, v132 row_half_mirror row_mask:0xf bank_mask:0xf bound_ctrl:1
	v_add_f32_dpp v133, v133, v133 row_half_mirror row_mask:0xf bank_mask:0xf bound_ctrl:1
	ds_read_b128 v[120:123], v137 offset:272
	ds_write_b32 v136, v132 offset:32512
	ds_write_b32 v136, v133 offset:32640
	s_waitcnt lgkmcnt(11)
	v_pk_mul_f32 v[132:133], v[104:105], v[36:37]
	v_pk_mul_f32 v[104:105], v[104:105], v[108:109]
	v_pk_fma_f32 v[132:133], v[38:39], v[106:107], v[132:133]
	v_pk_fma_f32 v[104:105], v[110:111], v[106:107], v[104:105]
	v_pk_fma_f32 v[132:133], v[32:33], v[112:113], v[132:133]
	v_pk_fma_f32 v[104:105], v[116:117], v[112:113], v[104:105]
	v_pk_fma_f32 v[132:133], v[34:35], v[114:115], v[132:133]
	v_pk_fma_f32 v[134:135], v[118:119], v[114:115], v[104:105]
	ds_read_b128 v[104:107], v137 offset:33280
	ds_read_b128 v[112:115], v137 offset:33296
	v_add_f32_e32 v132, v132, v133
	v_add_f32_e32 v133, v134, v135
	s_waitcnt lgkmcnt(10)
	v_pk_mul_f32 v[138:139], v[96:97], v[130:131] op_sel_hi:[1,0]
	v_add_f32_dpp v132, v132, v132 quad_perm:[1,0,3,2] row_mask:0xf bank_mask:0xf bound_ctrl:1
	v_add_f32_dpp v133, v133, v133 quad_perm:[1,0,3,2] row_mask:0xf bank_mask:0xf bound_ctrl:1
	v_pk_mul_f32 v[140:141], v[98:99], v[130:131] op_sel_hi:[1,0]
	v_pk_mul_f32 v[142:143], v[88:89], v[130:131] op_sel_hi:[1,0]
	v_pk_mul_f32 v[144:145], v[90:91], v[130:131] op_sel_hi:[1,0]
	v_mov_b32_e32 v130, v131
	v_add_f32_dpp v132, v132, v132 quad_perm:[2,3,0,1] row_mask:0xf bank_mask:0xf bound_ctrl:1
	v_add_f32_dpp v133, v133, v133 quad_perm:[2,3,0,1] row_mask:0xf bank_mask:0xf bound_ctrl:1
	v_pk_mul_f32 v[146:147], v[96:97], v[130:131] op_sel_hi:[1,0]
	v_add_f32_dpp v132, v132, v132 row_half_mirror row_mask:0xf bank_mask:0xf bound_ctrl:1
	v_add_f32_dpp v134, v133, v133 row_half_mirror row_mask:0xf bank_mask:0xf bound_ctrl:1
	v_pk_mul_f32 v[160:161], v[98:99], v[130:131] op_sel_hi:[1,0]
	s_waitcnt lgkmcnt(8)
	v_pk_fma_f32 v[138:139], v[132:133], v[100:101], v[138:139] op_sel_hi:[0,1,1]
	v_pk_fma_f32 v[140:141], v[132:133], v[102:103], v[140:141] op_sel_hi:[0,1,1]
	v_pk_fma_f32 v[142:143], v[132:133], v[92:93], v[142:143] op_sel_hi:[0,1,1]
	v_pk_fma_f32 v[132:133], v[132:133], v[94:95], v[144:145] op_sel_hi:[0,1,1]
	v_pk_fma_f32 v[144:145], v[134:135], v[100:101], v[146:147] op_sel_hi:[0,1,1]
	v_pk_mul_f32 v[162:163], v[88:89], v[130:131] op_sel_hi:[1,0]
	v_pk_fma_f32 v[146:147], v[134:135], v[102:103], v[160:161] op_sel_hi:[0,1,1]
	s_waitcnt lgkmcnt(7)
	v_pk_fma_f32 v[36:37], v[36:37], v[40:41], v[138:139]
	v_pk_fma_f32 v[40:41], v[108:109], v[40:41], v[144:145]
	v_pk_mul_f32 v[164:165], v[90:91], v[130:131] op_sel_hi:[1,0]
	ds_read_b128 v[88:91], v137 offset:8704
	ds_read_b128 v[96:99], v137 offset:8720
	ds_read2_b32 v[130:131], v136 offset0:64 offset1:96
	v_pk_fma_f32 v[160:161], v[134:135], v[92:93], v[162:163] op_sel_hi:[0,1,1]
	v_pk_fma_f32 v[38:39], v[38:39], v[42:43], v[140:141]
	s_waitcnt lgkmcnt(7)
	v_pk_fma_f32 v[34:35], v[34:35], v[46:47], v[132:133]
	v_pk_fma_f32 v[42:43], v[110:111], v[42:43], v[146:147]
	v_pk_mul_f32 v[132:133], v[124:125], v[36:37]
	v_pk_mul_f32 v[124:125], v[124:125], v[40:41]
	v_pk_fma_f32 v[134:135], v[134:135], v[94:95], v[164:165] op_sel_hi:[0,1,1]
	ds_read_b128 v[92:95], v137 offset:41472
	ds_read_b128 v[100:103], v137 offset:41488
	v_pk_fma_f32 v[32:33], v[32:33], v[44:45], v[142:143]
	v_pk_fma_f32 v[44:45], v[116:117], v[44:45], v[160:161]
	v_pk_fma_f32 v[132:133], v[38:39], v[126:127], v[132:133]
	v_pk_fma_f32 v[124:125], v[42:43], v[126:127], v[124:125]
	v_pk_fma_f32 v[46:47], v[118:119], v[46:47], v[134:135]
	v_pk_fma_f32 v[132:133], v[32:33], v[120:121], v[132:133]
	v_pk_fma_f32 v[120:121], v[44:45], v[120:121], v[124:125]
	v_pk_fma_f32 v[132:133], v[34:35], v[122:123], v[132:133]
	v_pk_fma_f32 v[134:135], v[46:47], v[122:123], v[120:121]
	v_add_f32_e32 v132, v132, v133
	v_add_f32_e32 v133, v134, v135
	ds_read_b128 v[108:111], v137 offset:25088
	v_add_f32_dpp v132, v132, v132 quad_perm:[1,0,3,2] row_mask:0xf bank_mask:0xf bound_ctrl:1
	v_add_f32_dpp v133, v133, v133 quad_perm:[1,0,3,2] row_mask:0xf bank_mask:0xf bound_ctrl:1
	ds_read_b128 v[116:119], v137 offset:25104
	v_add_f32_dpp v132, v132, v132 quad_perm:[2,3,0,1] row_mask:0xf bank_mask:0xf bound_ctrl:1
	v_add_f32_dpp v133, v133, v133 quad_perm:[2,3,0,1] row_mask:0xf bank_mask:0xf bound_ctrl:1
	ds_read_b128 v[120:123], v137 offset:512
	v_add_f32_dpp v132, v132, v132 row_half_mirror row_mask:0xf bank_mask:0xf bound_ctrl:1
	v_add_f32_dpp v133, v133, v133 row_half_mirror row_mask:0xf bank_mask:0xf bound_ctrl:1
	ds_read_b128 v[124:127], v137 offset:528
	ds_write_b32 v136, v132 offset:32768
	ds_write_b32 v136, v133 offset:32896
	s_waitcnt lgkmcnt(8)
	v_mov_b32_e32 v132, v131
	s_addk_i32 s14, 0x200
	s_cmpk_eq_i32 s14, 0x2000
	s_cbranch_scc0 .LBB0_493
	s_waitcnt lgkmcnt(0)
	s_barrier
	ds_read_b128 v[88:91], v195 offset:49152
	ds_read_b128 v[92:95], v195 offset:49168
	v_mov_b64_e32 v[106:107], v[86:87]
	v_mov_b64_e32 v[98:99], v[74:75]
	v_mov_b64_e32 v[110:111], v[78:79]
	s_waitcnt lgkmcnt(1)
	v_cvt_pk_bf16_f32 v88, v88, v89
	v_cvt_pk_bf16_f32 v89, v90, v91
	s_waitcnt lgkmcnt(0)
	v_cvt_pk_bf16_f32 v90, v92, v93
	v_lshlrev_b64 v[92:93], 10, v[128:129]
	v_cvt_pk_bf16_f32 v91, v94, v95
	v_lshl_add_u64 v[92:93], v[150:151], 0, v[92:93]
	global_store_dwordx4 v[92:93], v[88:91], off
	v_mov_b64_e32 v[114:115], v[82:83]
	s_cmp_eq_u32 s2, 64
	v_mov_b64_e32 v[90:91], v[70:71]
	v_mov_b64_e32 v[104:105], v[84:85]
	v_mov_b64_e32 v[88:89], v[68:69]
	v_mov_b64_e32 v[96:97], v[72:73]
	v_mov_b64_e32 v[108:109], v[76:77]
	v_mov_b64_e32 v[112:113], v[80:81]
	s_mov_b32 s15, s2
	s_cbranch_scc0 .LBB0_481
	s_setprio 0
	v_mov_b32_e32 v158, v222
	v_mov_b32_e32 v159, v223
	s_barrier
	s_branch .LBB0_395
